# convert_weights loops (P0 and L1 in-proj tail): finish() no longer waits for the just-issued next-item loads (vmcnt 7..0 -> 15..8, plus a drain on the no-next path)
# speedup vs baseline: 1.0036x; 1.0001x over previous
.LBB0_35:
	s_waitcnt vmcnt(0)
	s_cmpk_gt_i32 s18, 0x5ff
	s_mov_b64 s[6:7], -1
	s_cbranch_scc0 .LBB0_53
.LBB0_36:
	s_cmpk_gt_u32 s18, 0x7ff
	s_cbranch_scc0 .LBB0_46
	s_cmpk_gt_u32 s18, 0xd7f
	s_cbranch_scc0 .LBB0_43
	s_cmpk_gt_u32 s18, 0x12ff
	s_cbranch_scc0 .LBB0_40
	v_add_u32_e32 v78, v203, v226
	v_add_u32_e32 v79, 0x420, v78
	s_waitcnt vmcnt(15)
	ds_write2_b32 v78, v38, v39 offset1:1
	ds_write2_b32 v78, v40, v41 offset0:2 offset1:3
	s_waitcnt vmcnt(14)
	ds_write2_b32 v79, v34, v35 offset1:1
	v_add_u32_e32 v79, 0x428, v78
	ds_write2_b32 v79, v36, v37 offset1:1
	v_add_u32_e32 v79, 0x840, v78
	s_waitcnt vmcnt(13)
	ds_write2_b32 v79, v30, v31 offset1:1
	v_add_u32_e32 v79, 0x848, v78
	ds_write2_b32 v79, v32, v33 offset1:1
	v_add_u32_e32 v79, 0xc60, v78
	s_waitcnt vmcnt(12)
	ds_write2_b32 v79, v14, v15 offset1:1
	v_add_u32_e32 v79, 0xc68, v78
	ds_write2_b32 v79, v16, v17 offset1:1
	v_add_u32_e32 v79, 0x1080, v78
	s_waitcnt vmcnt(11)
	ds_write2_b32 v79, v22, v23 offset1:1
	v_add_u32_e32 v79, 0x1088, v78
	ds_write2_b32 v79, v24, v25 offset1:1
	v_add_u32_e32 v79, 0x14a0, v78
	s_waitcnt vmcnt(10)
	ds_write2_b32 v79, v6, v7 offset1:1
	v_add_u32_e32 v79, 0x14a8, v78
	ds_write2_b32 v79, v8, v9 offset1:1
	v_add_u32_e32 v79, 0x18c0, v78
	s_waitcnt vmcnt(9)
	ds_write2_b32 v79, v10, v11 offset1:1
	v_add_u32_e32 v79, 0x18c8, v78
	ds_write2_b32 v79, v12, v13 offset1:1
	v_add_u32_e32 v79, 0x1ce0, v78
	v_add_u32_e32 v78, 0x1ce8, v78
	s_waitcnt vmcnt(8)
	ds_write2_b32 v79, v2, v3 offset1:1
	ds_write2_b32 v78, v4, v5 offset1:1
	s_waitcnt lgkmcnt(0)
	ds_read2_b32 v[82:83], v76 offset1:8
	ds_read2_b32 v[86:87], v76 offset0:33 offset1:41
	ds_read2_b32 v[88:89], v76 offset0:66 offset1:74
	ds_read2_b32 v[90:91], v76 offset0:99 offset1:107
	ds_read2_b32 v[92:93], v76 offset0:132 offset1:140
	s_waitcnt lgkmcnt(4)
	v_bfe_u32 v78, v82, 16, 1
	v_add3_u32 v78, v82, v78, s13
	s_waitcnt lgkmcnt(3)
	v_bfe_u32 v79, v86, 16, 1
	v_lshrrev_b32_e32 v78, 16, v78
	v_add3_u32 v79, v86, v79, s13
	ds_read2_b32 v[94:95], v76 offset0:165 offset1:173
	v_and_or_b32 v78, v79, s16, v78
	s_waitcnt lgkmcnt(3)
	v_bfe_u32 v79, v88, 16, 1
	v_add3_u32 v79, v88, v79, s13
	s_waitcnt lgkmcnt(2)
	v_bfe_u32 v80, v90, 16, 1
	ds_read2_b32 v[96:97], v76 offset0:198 offset1:206
	v_lshrrev_b32_e32 v79, 16, v79
	v_add3_u32 v80, v90, v80, s13
	ds_read2_b32 v[98:99], v76 offset0:231 offset1:239
	v_and_or_b32 v79, v80, s16, v79
	s_waitcnt lgkmcnt(3)
	v_bfe_u32 v80, v92, 16, 1
	v_add3_u32 v80, v92, v80, s13
	s_waitcnt lgkmcnt(2)
	v_bfe_u32 v81, v94, 16, 1
	v_lshrrev_b32_e32 v80, 16, v80
	v_add3_u32 v81, v94, v81, s13
	v_and_or_b32 v80, v81, s16, v80
	s_waitcnt lgkmcnt(1)
	v_bfe_u32 v81, v96, 16, 1
	v_add3_u32 v81, v96, v81, s13
	s_waitcnt lgkmcnt(0)
	v_bfe_u32 v82, v98, 16, 1
	s_and_b32 s0, s12, 0xfc0
	s_and_b32 s6, s3, 0x3e0
	v_lshrrev_b32_e32 v81, 16, v81
	v_add3_u32 v82, v98, v82, s13
	s_lshl_b32 s0, s0, 1
	v_and_or_b32 v81, v82, s16, v81
	v_or_b32_e32 v82, s6, v199
	v_lshl_add_u64 v[84:85], v[68:69], 0, s[0:1]
	v_mul_u32_u24_e32 v100, 0x1600, v82
	v_mov_b32_e32 v101, v67
	v_lshl_add_u64 v[100:101], v[84:85], 0, v[100:101]
	global_store_dwordx4 v[100:101], v[78:81], off sc1
	v_bfe_u32 v82, v99, 16, 1
	v_add3_u32 v82, v99, v82, s13
	v_bfe_u32 v78, v83, 16, 1
	v_add3_u32 v78, v83, v78, s13
	v_bfe_u32 v79, v87, 16, 1
	v_lshrrev_b32_e32 v78, 16, v78
	v_add3_u32 v79, v87, v79, s13
	v_and_or_b32 v78, v79, s16, v78
	v_bfe_u32 v79, v89, 16, 1
	v_add3_u32 v79, v89, v79, s13
	v_bfe_u32 v80, v91, 16, 1
	v_lshrrev_b32_e32 v79, 16, v79
	v_add3_u32 v80, v91, v80, s13
	v_and_or_b32 v79, v80, s16, v79
	v_bfe_u32 v80, v93, 16, 1
	v_add3_u32 v80, v93, v80, s13
	v_bfe_u32 v81, v95, 16, 1
	v_lshrrev_b32_e32 v80, 16, v80
	v_add3_u32 v81, v95, v81, s13
	v_and_or_b32 v80, v81, s16, v80
	v_bfe_u32 v81, v97, 16, 1
	v_add3_u32 v81, v97, v81, s13
	v_lshrrev_b32_e32 v81, 16, v81
	v_and_or_b32 v81, v82, s16, v81
	v_or_b32_e32 v82, s6, v227
	v_mul_u32_u24_e32 v82, 0x1600, v82
	v_mov_b32_e32 v83, v67
	ds_read2_b32 v[86:87], v76 offset0:16 offset1:24
	v_lshl_add_u64 v[82:83], v[84:85], 0, v[82:83]
	global_store_dwordx4 v[82:83], v[78:81], off sc1
	ds_read2_b32 v[82:83], v76 offset0:49 offset1:57
	ds_read2_b32 v[88:89], v76 offset0:82 offset1:90
	ds_read2_b32 v[90:91], v76 offset0:115 offset1:123
	s_waitcnt lgkmcnt(3)
	v_bfe_u32 v78, v86, 16, 1
	v_add3_u32 v78, v86, v78, s13
	s_waitcnt lgkmcnt(2)
	v_bfe_u32 v79, v82, 16, 1
	ds_read2_b32 v[92:93], v76 offset0:148 offset1:156
	v_lshrrev_b32_e32 v78, 16, v78
	v_add3_u32 v79, v82, v79, s13
	ds_read2_b32 v[94:95], v76 offset0:181 offset1:189
	v_and_or_b32 v78, v79, s16, v78
	s_waitcnt lgkmcnt(3)
	v_bfe_u32 v79, v88, 16, 1
	v_add3_u32 v79, v88, v79, s13
	s_waitcnt lgkmcnt(2)
	v_bfe_u32 v80, v90, 16, 1
	ds_read2_b32 v[96:97], v76 offset0:214 offset1:222
	v_lshrrev_b32_e32 v79, 16, v79
	v_add3_u32 v80, v90, v80, s13
	ds_read2_b32 v[98:99], v76 offset0:247 offset1:255
	v_and_or_b32 v79, v80, s16, v79
	s_waitcnt lgkmcnt(3)
	v_bfe_u32 v80, v92, 16, 1
	v_add3_u32 v80, v92, v80, s13
	s_waitcnt lgkmcnt(2)
	v_bfe_u32 v81, v94, 16, 1
	v_lshrrev_b32_e32 v80, 16, v80
	v_add3_u32 v81, v94, v81, s13
	v_and_or_b32 v80, v81, s16, v80
	s_waitcnt lgkmcnt(1)
	v_bfe_u32 v81, v96, 16, 1
	v_add3_u32 v81, v96, v81, s13
	s_waitcnt lgkmcnt(0)
	v_bfe_u32 v82, v98, 16, 1
	v_lshrrev_b32_e32 v81, 16, v81
	v_add3_u32 v82, v98, v82, s13
	v_and_or_b32 v81, v82, s16, v81
	v_or_b32_e32 v82, s6, v228
	v_mul_u32_u24_e32 v100, 0x1600, v82
	v_mov_b32_e32 v101, v67
	v_lshl_add_u64 v[100:101], v[84:85], 0, v[100:101]
	global_store_dwordx4 v[100:101], v[78:81], off sc1
	v_bfe_u32 v82, v99, 16, 1
	v_add3_u32 v82, v99, v82, s13
	v_bfe_u32 v78, v87, 16, 1
	v_add3_u32 v78, v87, v78, s13
	v_bfe_u32 v79, v83, 16, 1
	v_lshrrev_b32_e32 v78, 16, v78
	v_add3_u32 v79, v83, v79, s13
	v_and_or_b32 v78, v79, s16, v78
	v_bfe_u32 v79, v89, 16, 1
	v_add3_u32 v79, v89, v79, s13
	v_bfe_u32 v80, v91, 16, 1
	v_lshrrev_b32_e32 v79, 16, v79
	v_add3_u32 v80, v91, v80, s13
	v_and_or_b32 v79, v80, s16, v79
	v_bfe_u32 v80, v93, 16, 1
	v_add3_u32 v80, v93, v80, s13
	v_bfe_u32 v81, v95, 16, 1
	v_lshrrev_b32_e32 v80, 16, v80
	v_add3_u32 v81, v95, v81, s13
	v_and_or_b32 v80, v81, s16, v80
	v_bfe_u32 v81, v97, 16, 1
	v_add3_u32 v81, v97, v81, s13
	v_lshrrev_b32_e32 v81, 16, v81
	v_and_or_b32 v81, v82, s16, v81
	v_or_b32_e32 v82, s6, v229
	v_mul_u32_u24_e32 v82, 0x1600, v82
	v_mov_b32_e32 v83, v67
	v_lshl_add_u64 v[82:83], v[84:85], 0, v[82:83]
	global_store_dwordx4 v[82:83], v[78:81], off sc1
	s_waitcnt lgkmcnt(0)
	s_mov_b64 s[6:7], 0
.LBB0_40:
	s_andn2_b64 vcc, exec, s[6:7]
	s_cbranch_vccnz .LBB0_42
	v_add_u32_e32 v78, v203, v226
	v_add_u32_e32 v79, 0x420, v78
	s_waitcnt vmcnt(15)
	ds_write2_b32 v78, v38, v39 offset1:1
	ds_write2_b32 v78, v40, v41 offset0:2 offset1:3
	s_waitcnt vmcnt(14)
	ds_write2_b32 v79, v34, v35 offset1:1
	v_add_u32_e32 v79, 0x428, v78
	ds_write2_b32 v79, v36, v37 offset1:1
	v_add_u32_e32 v79, 0x840, v78
	s_waitcnt vmcnt(13)
	ds_write2_b32 v79, v30, v31 offset1:1
	v_add_u32_e32 v79, 0x848, v78
	ds_write2_b32 v79, v32, v33 offset1:1
	v_add_u32_e32 v79, 0xc60, v78
	s_waitcnt vmcnt(12)
	ds_write2_b32 v79, v14, v15 offset1:1
	v_add_u32_e32 v79, 0xc68, v78
	ds_write2_b32 v79, v16, v17 offset1:1
	v_add_u32_e32 v79, 0x1080, v78
	s_waitcnt vmcnt(11)
	ds_write2_b32 v79, v22, v23 offset1:1
	v_add_u32_e32 v79, 0x1088, v78
	ds_write2_b32 v79, v24, v25 offset1:1
	v_add_u32_e32 v79, 0x14a0, v78
	s_waitcnt vmcnt(10)
	ds_write2_b32 v79, v6, v7 offset1:1
	v_add_u32_e32 v79, 0x14a8, v78
	ds_write2_b32 v79, v8, v9 offset1:1
	v_add_u32_e32 v79, 0x18c0, v78
	s_waitcnt vmcnt(9)
	ds_write2_b32 v79, v10, v11 offset1:1
	v_add_u32_e32 v79, 0x18c8, v78
	ds_write2_b32 v79, v12, v13 offset1:1
	v_add_u32_e32 v79, 0x1ce0, v78
	v_add_u32_e32 v78, 0x1ce8, v78
	s_waitcnt vmcnt(8)
	ds_write2_b32 v79, v2, v3 offset1:1
	ds_write2_b32 v78, v4, v5 offset1:1
	s_waitcnt lgkmcnt(0)
	ds_read2_b32 v[82:83], v76 offset1:8
	ds_read2_b32 v[86:87], v76 offset0:33 offset1:41
	ds_read2_b32 v[88:89], v76 offset0:66 offset1:74
	ds_read2_b32 v[90:91], v76 offset0:99 offset1:107
	ds_read2_b32 v[92:93], v76 offset0:132 offset1:140
	s_waitcnt lgkmcnt(4)
	v_bfe_u32 v78, v82, 16, 1
	v_add3_u32 v78, v82, v78, s13
	s_waitcnt lgkmcnt(3)
	v_bfe_u32 v79, v86, 16, 1
	s_add_i32 s0, s18, 0xf280
	v_lshrrev_b32_e32 v78, 16, v78
	v_add3_u32 v79, v86, v79, s13
	ds_read2_b32 v[94:95], v76 offset0:165 offset1:173
	s_and_b32 s6, s0, 0xffff
	v_and_or_b32 v78, v79, s16, v78
	s_waitcnt lgkmcnt(3)
	v_bfe_u32 v79, v88, 16, 1
	s_mul_i32 s6, s6, 0xba2f
	v_add3_u32 v79, v88, v79, s13
	s_waitcnt lgkmcnt(2)
	v_bfe_u32 v80, v90, 16, 1
	ds_read2_b32 v[96:97], v76 offset0:198 offset1:206
	s_lshr_b32 s7, s6, 22
	v_lshrrev_b32_e32 v79, 16, v79
	v_add3_u32 v80, v90, v80, s13
	ds_read2_b32 v[98:99], v76 offset0:231 offset1:239
	s_mulk_i32 s7, 0x58
	v_and_or_b32 v79, v80, s16, v79
	s_waitcnt lgkmcnt(3)
	v_bfe_u32 v80, v92, 16, 1
	s_sub_i32 s0, s0, s7
	v_add3_u32 v80, v92, v80, s13
	s_waitcnt lgkmcnt(2)
	v_bfe_u32 v81, v94, 16, 1
	s_lshl_b32 s7, s0, 5
	s_lshl_b32 s0, s0, 6
	v_lshrrev_b32_e32 v80, 16, v80
	v_add3_u32 v81, v94, v81, s13
	s_and_b32 s0, s0, 0x1f00
	s_and_b32 s7, s7, 0x60
	v_and_or_b32 v80, v81, s16, v80
	s_waitcnt lgkmcnt(1)
	v_bfe_u32 v81, v96, 16, 1
	s_or_b32 s0, s7, s0
	v_add3_u32 v81, v96, v81, s13
	s_waitcnt lgkmcnt(0)
	v_bfe_u32 v82, v98, 16, 1
	s_or_b32 s7, s0, 0x80
	s_lshr_b32 s0, s6, 15
	v_lshrrev_b32_e32 v81, 16, v81
	v_add3_u32 v82, v98, v82, s13
	s_and_b32 s0, s0, 0x1ff80
	v_and_or_b32 v81, v82, s16, v81
	v_or_b32_e32 v82, s7, v199
	v_lshl_add_u64 v[84:85], v[70:71], 0, s[0:1]
	v_lshlrev_b32_e32 v100, 11, v82
	v_mov_b32_e32 v101, v67
	v_lshl_add_u64 v[100:101], v[84:85], 0, v[100:101]
	global_store_dwordx4 v[100:101], v[78:81], off sc1
	v_bfe_u32 v82, v99, 16, 1
	v_add3_u32 v82, v99, v82, s13
	v_bfe_u32 v78, v83, 16, 1
	v_add3_u32 v78, v83, v78, s13
	v_bfe_u32 v79, v87, 16, 1
	v_lshrrev_b32_e32 v78, 16, v78
	v_add3_u32 v79, v87, v79, s13
	v_and_or_b32 v78, v79, s16, v78
	v_bfe_u32 v79, v89, 16, 1
	v_add3_u32 v79, v89, v79, s13
	v_bfe_u32 v80, v91, 16, 1
	v_lshrrev_b32_e32 v79, 16, v79
	v_add3_u32 v80, v91, v80, s13
	v_and_or_b32 v79, v80, s16, v79
	v_bfe_u32 v80, v93, 16, 1
	v_add3_u32 v80, v93, v80, s13
	v_bfe_u32 v81, v95, 16, 1
	v_lshrrev_b32_e32 v80, 16, v80
	v_add3_u32 v81, v95, v81, s13
	v_and_or_b32 v80, v81, s16, v80
	v_bfe_u32 v81, v97, 16, 1
	v_add3_u32 v81, v97, v81, s13
	v_lshrrev_b32_e32 v81, 16, v81
	v_and_or_b32 v81, v82, s16, v81
	v_or_b32_e32 v82, s7, v227
	v_lshlrev_b32_e32 v82, 11, v82
	v_mov_b32_e32 v83, v67
	ds_read2_b32 v[86:87], v76 offset0:16 offset1:24
	v_lshl_add_u64 v[82:83], v[84:85], 0, v[82:83]
	global_store_dwordx4 v[82:83], v[78:81], off sc1
	ds_read2_b32 v[82:83], v76 offset0:49 offset1:57
	ds_read2_b32 v[88:89], v76 offset0:82 offset1:90
	ds_read2_b32 v[90:91], v76 offset0:115 offset1:123
	s_waitcnt lgkmcnt(3)
	v_bfe_u32 v78, v86, 16, 1
	v_add3_u32 v78, v86, v78, s13
	s_waitcnt lgkmcnt(2)
	v_bfe_u32 v79, v82, 16, 1
	ds_read2_b32 v[92:93], v76 offset0:148 offset1:156
	v_lshrrev_b32_e32 v78, 16, v78
	v_add3_u32 v79, v82, v79, s13
	ds_read2_b32 v[94:95], v76 offset0:181 offset1:189
	v_and_or_b32 v78, v79, s16, v78
	s_waitcnt lgkmcnt(3)
	v_bfe_u32 v79, v88, 16, 1
	v_add3_u32 v79, v88, v79, s13
	s_waitcnt lgkmcnt(2)
	v_bfe_u32 v80, v90, 16, 1
	ds_read2_b32 v[96:97], v76 offset0:214 offset1:222
	v_lshrrev_b32_e32 v79, 16, v79
	v_add3_u32 v80, v90, v80, s13
	ds_read2_b32 v[98:99], v76 offset0:247 offset1:255
	v_and_or_b32 v79, v80, s16, v79
	s_waitcnt lgkmcnt(3)
	v_bfe_u32 v80, v92, 16, 1
	v_add3_u32 v80, v92, v80, s13
	s_waitcnt lgkmcnt(2)
	v_bfe_u32 v81, v94, 16, 1
	v_lshrrev_b32_e32 v80, 16, v80
	v_add3_u32 v81, v94, v81, s13
	v_and_or_b32 v80, v81, s16, v80
	s_waitcnt lgkmcnt(1)
	v_bfe_u32 v81, v96, 16, 1
	v_add3_u32 v81, v96, v81, s13
	s_waitcnt lgkmcnt(0)
	v_bfe_u32 v82, v98, 16, 1
	v_lshrrev_b32_e32 v81, 16, v81
	v_add3_u32 v82, v98, v82, s13
	v_and_or_b32 v81, v82, s16, v81
	v_or_b32_e32 v82, s7, v228
	v_lshlrev_b32_e32 v100, 11, v82
	v_mov_b32_e32 v101, v67
	v_lshl_add_u64 v[100:101], v[84:85], 0, v[100:101]
	global_store_dwordx4 v[100:101], v[78:81], off sc1
	v_bfe_u32 v82, v99, 16, 1
	v_add3_u32 v82, v99, v82, s13
	v_bfe_u32 v78, v87, 16, 1
	v_add3_u32 v78, v87, v78, s13
	v_bfe_u32 v79, v83, 16, 1
	v_lshrrev_b32_e32 v78, 16, v78
	v_add3_u32 v79, v83, v79, s13
	v_and_or_b32 v78, v79, s16, v78
	v_bfe_u32 v79, v89, 16, 1
	v_add3_u32 v79, v89, v79, s13
	v_bfe_u32 v80, v91, 16, 1
	v_lshrrev_b32_e32 v79, 16, v79
	v_add3_u32 v80, v91, v80, s13
	v_and_or_b32 v79, v80, s16, v79
	v_bfe_u32 v80, v93, 16, 1
	v_add3_u32 v80, v93, v80, s13
	v_bfe_u32 v81, v95, 16, 1
	v_lshrrev_b32_e32 v80, 16, v80
	v_add3_u32 v81, v95, v81, s13
	v_and_or_b32 v80, v81, s16, v80
	v_bfe_u32 v81, v97, 16, 1
	v_add3_u32 v81, v97, v81, s13
	v_lshrrev_b32_e32 v81, 16, v81
	v_and_or_b32 v81, v82, s16, v81
	v_or_b32_e32 v82, s7, v229
	v_lshlrev_b32_e32 v82, 11, v82
	v_mov_b32_e32 v83, v67
	v_lshl_add_u64 v[82:83], v[84:85], 0, v[82:83]
	global_store_dwordx4 v[82:83], v[78:81], off sc1
	s_waitcnt lgkmcnt(0)

.LBB0_43:
	s_andn2_b64 vcc, exec, s[6:7]
	s_cbranch_vccnz .LBB0_45
	v_add_u32_e32 v78, v203, v226
	v_add_u32_e32 v79, 0x420, v78
	s_waitcnt vmcnt(15)
	ds_write2_b32 v78, v38, v39 offset1:1
	ds_write2_b32 v78, v40, v41 offset0:2 offset1:3
	s_waitcnt vmcnt(14)
	ds_write2_b32 v79, v34, v35 offset1:1
	v_add_u32_e32 v79, 0x428, v78
	ds_write2_b32 v79, v36, v37 offset1:1
	v_add_u32_e32 v79, 0x840, v78
	s_waitcnt vmcnt(13)
	ds_write2_b32 v79, v30, v31 offset1:1
	v_add_u32_e32 v79, 0x848, v78
	ds_write2_b32 v79, v32, v33 offset1:1
	v_add_u32_e32 v79, 0xc60, v78
	s_waitcnt vmcnt(12)
	ds_write2_b32 v79, v14, v15 offset1:1
	v_add_u32_e32 v79, 0xc68, v78
	ds_write2_b32 v79, v16, v17 offset1:1
	v_add_u32_e32 v79, 0x1080, v78
	s_waitcnt vmcnt(11)
	ds_write2_b32 v79, v22, v23 offset1:1
	v_add_u32_e32 v79, 0x1088, v78
	ds_write2_b32 v79, v24, v25 offset1:1
	v_add_u32_e32 v79, 0x14a0, v78
	s_waitcnt vmcnt(10)
	ds_write2_b32 v79, v6, v7 offset1:1
	v_add_u32_e32 v79, 0x14a8, v78
	ds_write2_b32 v79, v8, v9 offset1:1
	v_add_u32_e32 v79, 0x18c0, v78
	s_waitcnt vmcnt(9)
	ds_write2_b32 v79, v10, v11 offset1:1
	v_add_u32_e32 v79, 0x18c8, v78
	ds_write2_b32 v79, v12, v13 offset1:1
	v_add_u32_e32 v79, 0x1ce0, v78
	v_add_u32_e32 v78, 0x1ce8, v78
	s_waitcnt vmcnt(8)
	ds_write2_b32 v79, v2, v3 offset1:1
	ds_write2_b32 v78, v4, v5 offset1:1
	s_waitcnt lgkmcnt(0)
	ds_read2_b32 v[82:83], v76 offset1:8
	ds_read2_b32 v[86:87], v76 offset0:33 offset1:41
	ds_read2_b32 v[88:89], v76 offset0:66 offset1:74
	ds_read2_b32 v[90:91], v76 offset0:99 offset1:107
	ds_read2_b32 v[92:93], v76 offset0:132 offset1:140
	s_waitcnt lgkmcnt(4)
	v_bfe_u32 v78, v82, 16, 1
	v_add3_u32 v78, v82, v78, s13
	s_waitcnt lgkmcnt(3)
	v_bfe_u32 v79, v86, 16, 1
	v_lshrrev_b32_e32 v78, 16, v78
	v_add3_u32 v79, v86, v79, s13
	ds_read2_b32 v[94:95], v76 offset0:165 offset1:173
	s_add_i32 s0, s18, 0xf800
	v_and_or_b32 v78, v79, s16, v78
	s_waitcnt lgkmcnt(3)
	v_bfe_u32 v79, v88, 16, 1
	s_and_b32 s6, s0, 0xffff
	v_add3_u32 v79, v88, v79, s13
	s_waitcnt lgkmcnt(2)
	v_bfe_u32 v80, v90, 16, 1
	ds_read2_b32 v[96:97], v76 offset0:198 offset1:206
	s_mul_i32 s6, s6, 0xba2f
	v_lshrrev_b32_e32 v79, 16, v79
	v_add3_u32 v80, v90, v80, s13
	ds_read2_b32 v[98:99], v76 offset0:231 offset1:239
	s_lshr_b32 s7, s6, 22
	v_and_or_b32 v79, v80, s16, v79
	s_waitcnt lgkmcnt(3)
	v_bfe_u32 v80, v92, 16, 1
	s_mulk_i32 s7, 0x58
	v_add3_u32 v80, v92, v80, s13
	s_waitcnt lgkmcnt(2)
	v_bfe_u32 v81, v94, 16, 1
	s_sub_i32 s0, s0, s7
	v_lshrrev_b32_e32 v80, 16, v80
	v_add3_u32 v81, v94, v81, s13
	s_lshl_b32 s7, s0, 5
	s_lshl_b32 s0, s0, 6
	v_and_or_b32 v80, v81, s16, v80
	s_waitcnt lgkmcnt(1)
	v_bfe_u32 v81, v96, 16, 1
	s_and_b32 s0, s0, 0x1f00
	s_and_b32 s7, s7, 0x60
	v_add3_u32 v81, v96, v81, s13
	s_waitcnt lgkmcnt(0)
	v_bfe_u32 v82, v98, 16, 1
	s_or_b32 s7, s0, s7
	s_lshr_b32 s0, s6, 15
	v_lshrrev_b32_e32 v81, 16, v81
	v_add3_u32 v82, v98, v82, s13
	s_and_b32 s0, s0, 0x1ff80
	v_and_or_b32 v81, v82, s16, v81
	v_or_b32_e32 v82, s7, v199
	v_lshl_add_u64 v[84:85], v[70:71], 0, s[0:1]
	v_lshlrev_b32_e32 v100, 11, v82
	v_mov_b32_e32 v101, v67
	v_lshl_add_u64 v[100:101], v[84:85], 0, v[100:101]
	global_store_dwordx4 v[100:101], v[78:81], off sc1
	v_bfe_u32 v82, v99, 16, 1
	v_add3_u32 v82, v99, v82, s13
	v_bfe_u32 v78, v83, 16, 1
	v_add3_u32 v78, v83, v78, s13
	v_bfe_u32 v79, v87, 16, 1
	v_lshrrev_b32_e32 v78, 16, v78
	v_add3_u32 v79, v87, v79, s13
	v_and_or_b32 v78, v79, s16, v78
	v_bfe_u32 v79, v89, 16, 1
	v_add3_u32 v79, v89, v79, s13
	v_bfe_u32 v80, v91, 16, 1
	v_lshrrev_b32_e32 v79, 16, v79
	v_add3_u32 v80, v91, v80, s13
	v_and_or_b32 v79, v80, s16, v79
	v_bfe_u32 v80, v93, 16, 1
	v_add3_u32 v80, v93, v80, s13
	v_bfe_u32 v81, v95, 16, 1
	v_lshrrev_b32_e32 v80, 16, v80
	v_add3_u32 v81, v95, v81, s13
	v_and_or_b32 v80, v81, s16, v80
	v_bfe_u32 v81, v97, 16, 1
	v_add3_u32 v81, v97, v81, s13
	v_lshrrev_b32_e32 v81, 16, v81
	v_and_or_b32 v81, v82, s16, v81
	v_or_b32_e32 v82, s7, v227
	v_lshlrev_b32_e32 v82, 11, v82
	v_mov_b32_e32 v83, v67
	ds_read2_b32 v[86:87], v76 offset0:16 offset1:24
	v_lshl_add_u64 v[82:83], v[84:85], 0, v[82:83]
	global_store_dwordx4 v[82:83], v[78:81], off sc1
	ds_read2_b32 v[82:83], v76 offset0:49 offset1:57
	ds_read2_b32 v[88:89], v76 offset0:82 offset1:90
	ds_read2_b32 v[90:91], v76 offset0:115 offset1:123
	s_waitcnt lgkmcnt(3)
	v_bfe_u32 v78, v86, 16, 1
	v_add3_u32 v78, v86, v78, s13
	s_waitcnt lgkmcnt(2)
	v_bfe_u32 v79, v82, 16, 1
	ds_read2_b32 v[92:93], v76 offset0:148 offset1:156
	v_lshrrev_b32_e32 v78, 16, v78
	v_add3_u32 v79, v82, v79, s13
	ds_read2_b32 v[94:95], v76 offset0:181 offset1:189
	v_and_or_b32 v78, v79, s16, v78
	s_waitcnt lgkmcnt(3)
	v_bfe_u32 v79, v88, 16, 1
	v_add3_u32 v79, v88, v79, s13
	s_waitcnt lgkmcnt(2)
	v_bfe_u32 v80, v90, 16, 1
	ds_read2_b32 v[96:97], v76 offset0:214 offset1:222
	v_lshrrev_b32_e32 v79, 16, v79
	v_add3_u32 v80, v90, v80, s13
	ds_read2_b32 v[98:99], v76 offset0:247 offset1:255
	v_and_or_b32 v79, v80, s16, v79
	s_waitcnt lgkmcnt(3)
	v_bfe_u32 v80, v92, 16, 1
	v_add3_u32 v80, v92, v80, s13
	s_waitcnt lgkmcnt(2)
	v_bfe_u32 v81, v94, 16, 1
	v_lshrrev_b32_e32 v80, 16, v80
	v_add3_u32 v81, v94, v81, s13
	v_and_or_b32 v80, v81, s16, v80
	s_waitcnt lgkmcnt(1)
	v_bfe_u32 v81, v96, 16, 1
	v_add3_u32 v81, v96, v81, s13
	s_waitcnt lgkmcnt(0)
	v_bfe_u32 v82, v98, 16, 1
	v_lshrrev_b32_e32 v81, 16, v81
	v_add3_u32 v82, v98, v82, s13
	v_and_or_b32 v81, v82, s16, v81
	v_or_b32_e32 v82, s7, v228
	v_lshlrev_b32_e32 v100, 11, v82
	v_mov_b32_e32 v101, v67
	v_lshl_add_u64 v[100:101], v[84:85], 0, v[100:101]
	global_store_dwordx4 v[100:101], v[78:81], off sc1
	v_bfe_u32 v82, v99, 16, 1
	v_add3_u32 v82, v99, v82, s13
	v_bfe_u32 v78, v87, 16, 1
	v_add3_u32 v78, v87, v78, s13
	v_bfe_u32 v79, v83, 16, 1
	v_lshrrev_b32_e32 v78, 16, v78
	v_add3_u32 v79, v83, v79, s13
	v_and_or_b32 v78, v79, s16, v78
	v_bfe_u32 v79, v89, 16, 1
	v_add3_u32 v79, v89, v79, s13
	v_bfe_u32 v80, v91, 16, 1
	v_lshrrev_b32_e32 v79, 16, v79
	v_add3_u32 v80, v91, v80, s13
	v_and_or_b32 v79, v80, s16, v79
	v_bfe_u32 v80, v93, 16, 1
	v_add3_u32 v80, v93, v80, s13
	v_bfe_u32 v81, v95, 16, 1
	v_lshrrev_b32_e32 v80, 16, v80
	v_add3_u32 v81, v95, v81, s13
	v_and_or_b32 v80, v81, s16, v80
	v_bfe_u32 v81, v97, 16, 1
	v_add3_u32 v81, v97, v81, s13
	v_lshrrev_b32_e32 v81, 16, v81
	v_and_or_b32 v81, v82, s16, v81
	v_or_b32_e32 v82, s7, v229
	v_lshlrev_b32_e32 v82, 11, v82
	v_mov_b32_e32 v83, v67
	v_lshl_add_u64 v[82:83], v[84:85], 0, v[82:83]
	global_store_dwordx4 v[82:83], v[78:81], off sc1
	s_waitcnt lgkmcnt(0)

.LBB0_46:
	s_andn2_b64 vcc, exec, s[6:7]
	s_cbranch_vccnz .LBB0_48
	v_add_u32_e32 v78, v203, v226
	v_add_u32_e32 v79, 0x420, v78
	s_waitcnt vmcnt(15)
	ds_write2_b32 v78, v38, v39 offset1:1
	ds_write2_b32 v78, v40, v41 offset0:2 offset1:3
	s_waitcnt vmcnt(14)
	ds_write2_b32 v79, v34, v35 offset1:1
	v_add_u32_e32 v79, 0x428, v78
	ds_write2_b32 v79, v36, v37 offset1:1
	v_add_u32_e32 v79, 0x840, v78
	s_waitcnt vmcnt(13)
	ds_write2_b32 v79, v30, v31 offset1:1
	v_add_u32_e32 v79, 0x848, v78
	ds_write2_b32 v79, v32, v33 offset1:1
	v_add_u32_e32 v79, 0xc60, v78
	s_waitcnt vmcnt(12)
	ds_write2_b32 v79, v14, v15 offset1:1
	v_add_u32_e32 v79, 0xc68, v78
	ds_write2_b32 v79, v16, v17 offset1:1
	v_add_u32_e32 v79, 0x1080, v78
	s_waitcnt vmcnt(11)
	ds_write2_b32 v79, v22, v23 offset1:1
	v_add_u32_e32 v79, 0x1088, v78
	ds_write2_b32 v79, v24, v25 offset1:1
	v_add_u32_e32 v79, 0x14a0, v78
	s_waitcnt vmcnt(10)
	ds_write2_b32 v79, v6, v7 offset1:1
	v_add_u32_e32 v79, 0x14a8, v78
	ds_write2_b32 v79, v8, v9 offset1:1
	v_add_u32_e32 v79, 0x18c0, v78
	s_waitcnt vmcnt(9)
	ds_write2_b32 v79, v10, v11 offset1:1
	v_add_u32_e32 v79, 0x18c8, v78
	ds_write2_b32 v79, v12, v13 offset1:1
	v_add_u32_e32 v79, 0x1ce0, v78
	v_add_u32_e32 v78, 0x1ce8, v78
	s_waitcnt vmcnt(8)
	ds_write2_b32 v79, v2, v3 offset1:1
	ds_write2_b32 v78, v4, v5 offset1:1
	s_waitcnt lgkmcnt(0)
	ds_read2_b32 v[82:83], v76 offset1:8
	ds_read2_b32 v[86:87], v76 offset0:33 offset1:41
	ds_read2_b32 v[88:89], v76 offset0:66 offset1:74
	ds_read2_b32 v[90:91], v76 offset0:99 offset1:107
	ds_read2_b32 v[92:93], v76 offset0:132 offset1:140
	s_waitcnt lgkmcnt(4)
	v_bfe_u32 v78, v82, 16, 1
	v_add3_u32 v78, v82, v78, s13
	s_waitcnt lgkmcnt(3)
	v_bfe_u32 v79, v86, 16, 1
	v_lshrrev_b32_e32 v78, 16, v78
	v_add3_u32 v79, v86, v79, s13
	ds_read2_b32 v[94:95], v76 offset0:165 offset1:173
	v_and_or_b32 v78, v79, s16, v78
	s_waitcnt lgkmcnt(3)
	v_bfe_u32 v79, v88, 16, 1
	v_add3_u32 v79, v88, v79, s13
	s_waitcnt lgkmcnt(2)
	v_bfe_u32 v80, v90, 16, 1
	ds_read2_b32 v[96:97], v76 offset0:198 offset1:206
	v_lshrrev_b32_e32 v79, 16, v79
	v_add3_u32 v80, v90, v80, s13
	ds_read2_b32 v[98:99], v76 offset0:231 offset1:239
	v_and_or_b32 v79, v80, s16, v79
	s_waitcnt lgkmcnt(3)
	v_bfe_u32 v80, v92, 16, 1
	v_add3_u32 v80, v92, v80, s13
	s_waitcnt lgkmcnt(2)
	v_bfe_u32 v81, v94, 16, 1
	v_lshrrev_b32_e32 v80, 16, v80
	v_add3_u32 v81, v94, v81, s13
	v_and_or_b32 v80, v81, s16, v80
	s_waitcnt lgkmcnt(1)
	v_bfe_u32 v81, v96, 16, 1
	s_add_i32 s0, s12, 0x1a00
	s_add_i32 s6, s3, 0x1a000
	v_add3_u32 v81, v96, v81, s13
	s_waitcnt lgkmcnt(0)
	v_bfe_u32 v82, v98, 16, 1
	s_and_b32 s0, s0, 0xfc0
	s_and_b32 s6, s6, 0x3e0
	v_lshrrev_b32_e32 v81, 16, v81
	v_add3_u32 v82, v98, v82, s13
	s_lshl_b32 s0, s0, 1
	v_and_or_b32 v81, v82, s16, v81
	v_or_b32_e32 v82, s6, v199
	v_lshl_add_u64 v[84:85], v[72:73], 0, s[0:1]
	v_lshlrev_b32_e32 v100, 11, v82
	v_mov_b32_e32 v101, v67
	v_lshl_add_u64 v[100:101], v[84:85], 0, v[100:101]
	global_store_dwordx4 v[100:101], v[78:81], off sc1
	v_bfe_u32 v82, v99, 16, 1
	v_add3_u32 v82, v99, v82, s13
	v_bfe_u32 v78, v83, 16, 1
	v_add3_u32 v78, v83, v78, s13
	v_bfe_u32 v79, v87, 16, 1
	v_lshrrev_b32_e32 v78, 16, v78
	v_add3_u32 v79, v87, v79, s13
	v_and_or_b32 v78, v79, s16, v78
	v_bfe_u32 v79, v89, 16, 1
	v_add3_u32 v79, v89, v79, s13
	v_bfe_u32 v80, v91, 16, 1
	v_lshrrev_b32_e32 v79, 16, v79
	v_add3_u32 v80, v91, v80, s13
	v_and_or_b32 v79, v80, s16, v79
	v_bfe_u32 v80, v93, 16, 1
	v_add3_u32 v80, v93, v80, s13
	v_bfe_u32 v81, v95, 16, 1
	v_lshrrev_b32_e32 v80, 16, v80
	v_add3_u32 v81, v95, v81, s13
	v_and_or_b32 v80, v81, s16, v80
	v_bfe_u32 v81, v97, 16, 1
	v_add3_u32 v81, v97, v81, s13
	v_lshrrev_b32_e32 v81, 16, v81
	v_and_or_b32 v81, v82, s16, v81
	v_or_b32_e32 v82, s6, v227
	v_lshlrev_b32_e32 v82, 11, v82
	v_mov_b32_e32 v83, v67
	ds_read2_b32 v[86:87], v76 offset0:16 offset1:24
	v_lshl_add_u64 v[82:83], v[84:85], 0, v[82:83]
	global_store_dwordx4 v[82:83], v[78:81], off sc1
	ds_read2_b32 v[82:83], v76 offset0:49 offset1:57
	ds_read2_b32 v[88:89], v76 offset0:82 offset1:90
	ds_read2_b32 v[90:91], v76 offset0:115 offset1:123
	s_waitcnt lgkmcnt(3)
	v_bfe_u32 v78, v86, 16, 1
	v_add3_u32 v78, v86, v78, s13
	s_waitcnt lgkmcnt(2)
	v_bfe_u32 v79, v82, 16, 1
	ds_read2_b32 v[92:93], v76 offset0:148 offset1:156
	v_lshrrev_b32_e32 v78, 16, v78
	v_add3_u32 v79, v82, v79, s13
	ds_read2_b32 v[94:95], v76 offset0:181 offset1:189
	v_and_or_b32 v78, v79, s16, v78
	s_waitcnt lgkmcnt(3)
	v_bfe_u32 v79, v88, 16, 1
	v_add3_u32 v79, v88, v79, s13
	s_waitcnt lgkmcnt(2)
	v_bfe_u32 v80, v90, 16, 1
	ds_read2_b32 v[96:97], v76 offset0:214 offset1:222
	v_lshrrev_b32_e32 v79, 16, v79
	v_add3_u32 v80, v90, v80, s13
	ds_read2_b32 v[98:99], v76 offset0:247 offset1:255
	v_and_or_b32 v79, v80, s16, v79
	s_waitcnt lgkmcnt(3)
	v_bfe_u32 v80, v92, 16, 1
	v_add3_u32 v80, v92, v80, s13
	s_waitcnt lgkmcnt(2)
	v_bfe_u32 v81, v94, 16, 1
	v_lshrrev_b32_e32 v80, 16, v80
	v_add3_u32 v81, v94, v81, s13
	v_and_or_b32 v80, v81, s16, v80
	s_waitcnt lgkmcnt(1)
	v_bfe_u32 v81, v96, 16, 1
	v_add3_u32 v81, v96, v81, s13
	s_waitcnt lgkmcnt(0)
	v_bfe_u32 v82, v98, 16, 1
	v_lshrrev_b32_e32 v81, 16, v81
	v_add3_u32 v82, v98, v82, s13
	v_and_or_b32 v81, v82, s16, v81
	v_or_b32_e32 v82, s6, v228
	v_lshlrev_b32_e32 v100, 11, v82
	v_mov_b32_e32 v101, v67
	v_lshl_add_u64 v[100:101], v[84:85], 0, v[100:101]
	global_store_dwordx4 v[100:101], v[78:81], off sc1
	v_bfe_u32 v82, v99, 16, 1
	v_add3_u32 v82, v99, v82, s13
	v_bfe_u32 v78, v87, 16, 1
	v_add3_u32 v78, v87, v78, s13
	v_bfe_u32 v79, v83, 16, 1
	v_lshrrev_b32_e32 v78, 16, v78
	v_add3_u32 v79, v83, v79, s13
	v_and_or_b32 v78, v79, s16, v78
	v_bfe_u32 v79, v89, 16, 1
	v_add3_u32 v79, v89, v79, s13
	v_bfe_u32 v80, v91, 16, 1
	v_lshrrev_b32_e32 v79, 16, v79
	v_add3_u32 v80, v91, v80, s13
	v_and_or_b32 v79, v80, s16, v79
	v_bfe_u32 v80, v93, 16, 1
	v_add3_u32 v80, v93, v80, s13
	v_bfe_u32 v81, v95, 16, 1
	v_lshrrev_b32_e32 v80, 16, v80
	v_add3_u32 v81, v95, v81, s13
	v_and_or_b32 v80, v81, s16, v80
	v_bfe_u32 v81, v97, 16, 1
	v_add3_u32 v81, v97, v81, s13
	v_lshrrev_b32_e32 v81, 16, v81
	v_and_or_b32 v81, v82, s16, v81
	v_or_b32_e32 v82, s6, v229
	v_lshlrev_b32_e32 v82, 11, v82
	v_mov_b32_e32 v83, v67
	v_lshl_add_u64 v[82:83], v[84:85], 0, v[82:83]
	global_store_dwordx4 v[82:83], v[78:81], off sc1
	s_waitcnt lgkmcnt(0)

.LBB0_54:
	s_mul_hi_i32 s0, s18, 0x2aaaaaab
	s_lshr_b32 s6, s0, 31
	s_ashr_i32 s0, s0, 4
	s_add_i32 s0, s0, s6
	s_mul_i32 s6, s0, 0xffffffa0
	s_add_i32 s7, s18, s6
	s_lshl_b32 s6, s0, 6
	s_cmp_lt_i32 s7, 16
	s_cselect_b64 s[8:9], -1, 0
	s_and_b32 s7, s7, 0x3fffff0
	s_cmp_eq_u32 s7, 48
	s_cselect_b64 s[10:11], -1, 0
	s_or_b64 vcc, s[8:9], s[10:11]
	v_cndmask_b32_e32 v78, 1.0, v77, vcc
	s_waitcnt vmcnt(15)
	v_pk_mul_f32 v[38:39], v[78:79], v[38:39] op_sel_hi:[0,1]
	v_add_u32_e32 v79, v203, v226
	ds_write2_b32 v79, v38, v39 offset1:1
	v_pk_mul_f32 v[38:39], v[78:79], v[40:41] op_sel_hi:[0,1]
	ds_write2_b32 v79, v38, v39 offset0:2 offset1:3
	s_waitcnt vmcnt(14)
	v_pk_mul_f32 v[34:35], v[78:79], v[34:35] op_sel_hi:[0,1]
	v_add_u32_e32 v38, 0x420, v79
	ds_write2_b32 v38, v34, v35 offset1:1
	v_pk_mul_f32 v[34:35], v[78:79], v[36:37] op_sel_hi:[0,1]
	v_add_u32_e32 v36, 0x428, v79
	ds_write2_b32 v36, v34, v35 offset1:1
	s_waitcnt vmcnt(13)
	v_pk_mul_f32 v[30:31], v[78:79], v[30:31] op_sel_hi:[0,1]
	v_add_u32_e32 v34, 0x840, v79
	ds_write2_b32 v34, v30, v31 offset1:1
	v_pk_mul_f32 v[30:31], v[78:79], v[32:33] op_sel_hi:[0,1]
	v_add_u32_e32 v32, 0x848, v79
	ds_write2_b32 v32, v30, v31 offset1:1
	s_waitcnt vmcnt(12)
	v_pk_mul_f32 v[14:15], v[78:79], v[14:15] op_sel_hi:[0,1]
	v_add_u32_e32 v30, 0xc60, v79
	ds_write2_b32 v30, v14, v15 offset1:1
	v_pk_mul_f32 v[14:15], v[78:79], v[16:17] op_sel_hi:[0,1]
	v_add_u32_e32 v16, 0xc68, v79
	ds_write2_b32 v16, v14, v15 offset1:1
	s_waitcnt vmcnt(11)
	v_pk_mul_f32 v[14:15], v[22:23], v[78:79] op_sel_hi:[1,0]
	v_add_u32_e32 v16, 0x1080, v79
	ds_write2_b32 v16, v14, v15 offset1:1
	v_pk_mul_f32 v[14:15], v[24:25], v[78:79] op_sel_hi:[1,0]
	v_add_u32_e32 v16, 0x1088, v79
	ds_write2_b32 v16, v14, v15 offset1:1
	s_waitcnt vmcnt(10)
	v_pk_mul_f32 v[6:7], v[6:7], v[78:79] op_sel_hi:[1,0]
	v_add_u32_e32 v14, 0x14a0, v79
	ds_write2_b32 v14, v6, v7 offset1:1
	v_pk_mul_f32 v[6:7], v[8:9], v[78:79] op_sel_hi:[1,0]
	v_add_u32_e32 v8, 0x14a8, v79
	ds_write2_b32 v8, v6, v7 offset1:1
	s_waitcnt vmcnt(9)
	v_pk_mul_f32 v[6:7], v[10:11], v[78:79] op_sel_hi:[1,0]
	v_add_u32_e32 v8, 0x18c0, v79
	ds_write2_b32 v8, v6, v7 offset1:1
	v_pk_mul_f32 v[6:7], v[12:13], v[78:79] op_sel_hi:[1,0]
	v_add_u32_e32 v8, 0x18c8, v79
	ds_write2_b32 v8, v6, v7 offset1:1
	s_waitcnt vmcnt(8)
	v_pk_mul_f32 v[2:3], v[2:3], v[78:79] op_sel_hi:[1,0]
	v_add_u32_e32 v6, 0x1ce0, v79
	ds_write2_b32 v6, v2, v3 offset1:1
	v_pk_mul_f32 v[2:3], v[4:5], v[78:79] op_sel_hi:[1,0]
	v_add_u32_e32 v4, 0x1ce8, v79
	ds_write2_b32 v4, v2, v3 offset1:1
	s_waitcnt lgkmcnt(0)
	ds_read2_b32 v[6:7], v76 offset1:8
	ds_read2_b32 v[10:11], v76 offset0:33 offset1:41
	ds_read2_b32 v[12:13], v76 offset0:66 offset1:74
	ds_read2_b32 v[14:15], v76 offset0:99 offset1:107
	ds_read2_b32 v[16:17], v76 offset0:132 offset1:140
	s_waitcnt lgkmcnt(4)
	v_bfe_u32 v2, v6, 16, 1
	v_add3_u32 v2, v6, v2, s13
	s_waitcnt lgkmcnt(3)
	v_bfe_u32 v3, v10, 16, 1
	v_lshrrev_b32_e32 v2, 16, v2
	v_add3_u32 v3, v10, v3, s13
	ds_read2_b32 v[22:23], v76 offset0:165 offset1:173
	v_and_or_b32 v2, v3, s16, v2
	s_waitcnt lgkmcnt(3)
	v_bfe_u32 v3, v12, 16, 1
	v_add3_u32 v3, v12, v3, s13
	s_waitcnt lgkmcnt(2)
	v_bfe_u32 v4, v14, 16, 1
	ds_read2_b32 v[24:25], v76 offset0:198 offset1:206
	v_lshrrev_b32_e32 v3, 16, v3
	v_add3_u32 v4, v14, v4, s13
	ds_read2_b32 v[30:31], v76 offset0:231 offset1:239
	v_and_or_b32 v3, v4, s16, v3
	s_waitcnt lgkmcnt(3)
	v_bfe_u32 v4, v16, 16, 1
	s_mulk_i32 s0, 0xf400
	v_add3_u32 v4, v16, v4, s13
	s_waitcnt lgkmcnt(2)
	v_bfe_u32 v5, v22, 16, 1
	s_add_i32 s0, s0, s3
	v_lshrrev_b32_e32 v4, 16, v4
	v_add3_u32 v5, v22, v5, s13
	v_add_u32_e32 v34, s0, v199
	v_and_or_b32 v4, v5, s16, v4
	s_waitcnt lgkmcnt(1)
	v_bfe_u32 v5, v24, 16, 1
	v_add_u32_e32 v32, 0x26000, v34
	s_ashr_i32 s7, s6, 31
	v_add3_u32 v5, v24, v5, s13
	s_waitcnt lgkmcnt(0)
	v_bfe_u32 v6, v30, 16, 1
	v_ashrrev_i32_e32 v33, 31, v32
	v_lshl_add_u64 v[8:9], s[6:7], 1, v[74:75]
	v_lshrrev_b32_e32 v5, 16, v5
	v_add3_u32 v6, v30, v6, s13
	v_lshlrev_b64 v[32:33], 11, v[32:33]
	v_and_or_b32 v5, v6, s16, v5
	v_lshl_add_u64 v[32:33], v[8:9], 0, v[32:33]
	global_store_dwordx4 v[32:33], v[2:5], off sc1
	v_bfe_u32 v6, v31, 16, 1
	v_add3_u32 v6, v31, v6, s13
	v_bfe_u32 v2, v7, 16, 1
	v_add3_u32 v2, v7, v2, s13
	v_bfe_u32 v3, v11, 16, 1
	v_lshrrev_b32_e32 v2, 16, v2
	v_add3_u32 v3, v11, v3, s13
	v_and_or_b32 v2, v3, s16, v2
	v_bfe_u32 v3, v13, 16, 1
	v_add3_u32 v3, v13, v3, s13
	v_bfe_u32 v4, v15, 16, 1
	v_lshrrev_b32_e32 v3, 16, v3
	v_add3_u32 v4, v15, v4, s13
	v_and_or_b32 v3, v4, s16, v3
	v_bfe_u32 v4, v17, 16, 1
	v_add3_u32 v4, v17, v4, s13
	v_bfe_u32 v5, v23, 16, 1
	v_lshrrev_b32_e32 v4, 16, v4
	v_add3_u32 v5, v23, v5, s13
	v_and_or_b32 v4, v5, s16, v4
	v_bfe_u32 v5, v25, 16, 1
	v_add3_u32 v5, v25, v5, s13
	v_lshrrev_b32_e32 v5, 16, v5
	v_and_or_b32 v5, v6, s16, v5
	v_add_u32_e32 v6, 0x26008, v34
	v_ashrrev_i32_e32 v7, 31, v6
	v_lshlrev_b64 v[6:7], 11, v[6:7]
	ds_read2_b32 v[10:11], v76 offset0:16 offset1:24
	v_lshl_add_u64 v[6:7], v[8:9], 0, v[6:7]
	global_store_dwordx4 v[6:7], v[2:5], off sc1
	ds_read2_b32 v[6:7], v76 offset0:49 offset1:57
	ds_read2_b32 v[12:13], v76 offset0:82 offset1:90
	ds_read2_b32 v[14:15], v76 offset0:115 offset1:123
	s_waitcnt lgkmcnt(3)
	v_bfe_u32 v2, v10, 16, 1
	v_add3_u32 v2, v10, v2, s13
	s_waitcnt lgkmcnt(2)
	v_bfe_u32 v3, v6, 16, 1
	ds_read2_b32 v[16:17], v76 offset0:148 offset1:156
	v_lshrrev_b32_e32 v2, 16, v2
	v_add3_u32 v3, v6, v3, s13
	ds_read2_b32 v[22:23], v76 offset0:181 offset1:189
	v_and_or_b32 v2, v3, s16, v2
	s_waitcnt lgkmcnt(3)
	v_bfe_u32 v3, v12, 16, 1
	v_add3_u32 v3, v12, v3, s13
	s_waitcnt lgkmcnt(2)
	v_bfe_u32 v4, v14, 16, 1
	ds_read2_b32 v[24:25], v76 offset0:214 offset1:222
	v_lshrrev_b32_e32 v3, 16, v3
	v_add3_u32 v4, v14, v4, s13
	ds_read2_b32 v[30:31], v76 offset0:247 offset1:255
	v_and_or_b32 v3, v4, s16, v3
	s_waitcnt lgkmcnt(3)
	v_bfe_u32 v4, v16, 16, 1
	v_add3_u32 v4, v16, v4, s13
	s_waitcnt lgkmcnt(2)
	v_bfe_u32 v5, v22, 16, 1
	v_lshrrev_b32_e32 v4, 16, v4
	v_add3_u32 v5, v22, v5, s13
	v_and_or_b32 v4, v5, s16, v4
	s_waitcnt lgkmcnt(1)
	v_bfe_u32 v5, v24, 16, 1
	v_add_u32_e32 v32, 0x26010, v34
	v_add3_u32 v5, v24, v5, s13
	s_waitcnt lgkmcnt(0)
	v_bfe_u32 v6, v30, 16, 1
	v_ashrrev_i32_e32 v33, 31, v32
	v_lshrrev_b32_e32 v5, 16, v5
	v_add3_u32 v6, v30, v6, s13
	v_lshlrev_b64 v[32:33], 11, v[32:33]
	v_and_or_b32 v5, v6, s16, v5
	v_lshl_add_u64 v[32:33], v[8:9], 0, v[32:33]
	global_store_dwordx4 v[32:33], v[2:5], off sc1
	v_bfe_u32 v6, v31, 16, 1
	v_add3_u32 v6, v31, v6, s13
	v_bfe_u32 v2, v11, 16, 1
	v_add3_u32 v2, v11, v2, s13
	v_bfe_u32 v3, v7, 16, 1
	v_lshrrev_b32_e32 v2, 16, v2
	v_add3_u32 v3, v7, v3, s13
	v_and_or_b32 v2, v3, s16, v2
	v_bfe_u32 v3, v13, 16, 1
	v_add3_u32 v3, v13, v3, s13
	v_bfe_u32 v4, v15, 16, 1
	v_lshrrev_b32_e32 v3, 16, v3
	v_add3_u32 v4, v15, v4, s13
	v_and_or_b32 v3, v4, s16, v3
	v_bfe_u32 v4, v17, 16, 1
	v_add3_u32 v4, v17, v4, s13
	v_bfe_u32 v5, v23, 16, 1
	v_lshrrev_b32_e32 v4, 16, v4
	v_add3_u32 v5, v23, v5, s13
	v_and_or_b32 v4, v5, s16, v4
	v_bfe_u32 v5, v25, 16, 1
	v_add3_u32 v5, v25, v5, s13
	v_lshrrev_b32_e32 v5, 16, v5
	v_and_or_b32 v5, v6, s16, v5
	v_add_u32_e32 v6, 0x26018, v34
	v_ashrrev_i32_e32 v7, 31, v6
	v_lshlrev_b64 v[6:7], 11, v[6:7]
	v_lshl_add_u64 v[6:7], v[8:9], 0, v[6:7]
	global_store_dwordx4 v[6:7], v[2:5], off sc1
	s_waitcnt lgkmcnt(0)
	s_branch .LBB0_27

.LBB0_1018:
	s_waitcnt vmcnt(0)
	s_cmpk_gt_i32 s25, 0x5ff
	s_mov_b64 s[10:11], -1
	s_cbranch_scc0 .LBB0_1032
.LBB0_1019:
	s_cmpk_gt_u32 s25, 0x7ff
	s_cbranch_scc0 .LBB0_1025
	v_add_u32_e32 v77, v203, v226
	v_add_u32_e32 v78, 0x420, v77
	s_waitcnt vmcnt(15)
	ds_write2_b32 v77, v54, v55 offset1:1
	ds_write2_b32 v77, v56, v57 offset0:2 offset1:3
	s_waitcnt vmcnt(14)
	ds_write2_b32 v78, v50, v51 offset1:1
	v_add_u32_e32 v78, 0x428, v77
	ds_write2_b32 v78, v52, v53 offset1:1
	v_add_u32_e32 v78, 0x840, v77
	s_waitcnt vmcnt(13)
	ds_write2_b32 v78, v42, v43 offset1:1
	v_add_u32_e32 v78, 0x848, v77
	ds_write2_b32 v78, v44, v45 offset1:1
	v_add_u32_e32 v78, 0xc60, v77
	s_waitcnt vmcnt(12)
	ds_write2_b32 v78, v30, v31 offset1:1
	v_add_u32_e32 v78, 0xc68, v77
	ds_write2_b32 v78, v32, v33 offset1:1
	v_add_u32_e32 v78, 0x1080, v77
	s_waitcnt vmcnt(11)
	ds_write2_b32 v78, v34, v35 offset1:1
	v_add_u32_e32 v78, 0x1088, v77
	ds_write2_b32 v78, v36, v37 offset1:1
	v_add_u32_e32 v78, 0x14a0, v77
	s_waitcnt vmcnt(10)
	ds_write2_b32 v78, v22, v23 offset1:1
	v_add_u32_e32 v78, 0x14a8, v77
	ds_write2_b32 v78, v24, v25 offset1:1
	v_add_u32_e32 v78, 0x18c0, v77
	s_waitcnt vmcnt(9)
	ds_write2_b32 v78, v26, v27 offset1:1
	v_add_u32_e32 v78, 0x18c8, v77
	s_cmpk_gt_u32 s25, 0xd7f
	ds_write2_b32 v78, v28, v29 offset1:1
	v_add_u32_e32 v78, 0x1ce0, v77
	v_add_u32_e32 v77, 0x1ce8, v77
	s_waitcnt vmcnt(8)
	ds_write2_b32 v78, v10, v11 offset1:1
	ds_write2_b32 v77, v12, v13 offset1:1
	s_cbranch_scc0 .LBB0_1022
	s_waitcnt lgkmcnt(0)
	ds_read2_b32 v[82:83], v75 offset1:8
	ds_read2_b32 v[86:87], v75 offset0:33 offset1:41
	ds_read2_b32 v[88:89], v75 offset0:66 offset1:74
	ds_read2_b32 v[90:91], v75 offset0:99 offset1:107
	ds_read2_b32 v[92:93], v75 offset0:132 offset1:140
	s_waitcnt lgkmcnt(4)
	v_bfe_u32 v77, v82, 16, 1
	v_add3_u32 v77, v82, v77, s22
	s_waitcnt lgkmcnt(3)
	v_bfe_u32 v78, v86, 16, 1
	s_add_i32 s6, s25, 0xf280
	v_lshrrev_b32_e32 v77, 16, v77
	v_add3_u32 v78, v86, v78, s22
	ds_read2_b32 v[94:95], v75 offset0:165 offset1:173
	s_and_b32 s10, s6, 0xffff
	v_and_or_b32 v78, v78, s23, v77
	s_waitcnt lgkmcnt(3)
	v_bfe_u32 v77, v88, 16, 1
	s_mul_i32 s10, s10, 0xba2f
	v_add3_u32 v77, v88, v77, s22
	s_waitcnt lgkmcnt(2)
	v_bfe_u32 v79, v90, 16, 1
	ds_read2_b32 v[96:97], v75 offset0:198 offset1:206
	s_lshr_b32 s11, s10, 22
	v_lshrrev_b32_e32 v77, 16, v77
	v_add3_u32 v79, v90, v79, s22
	ds_read2_b32 v[98:99], v75 offset0:231 offset1:239
	s_mulk_i32 s11, 0x58
	v_and_or_b32 v79, v79, s23, v77
	s_waitcnt lgkmcnt(3)
	v_bfe_u32 v77, v92, 16, 1
	s_sub_i32 s6, s6, s11
	v_add3_u32 v77, v92, v77, s22
	s_waitcnt lgkmcnt(2)
	v_bfe_u32 v80, v94, 16, 1
	s_lshl_b32 s11, s6, 5
	s_lshl_b32 s6, s6, 6
	v_lshrrev_b32_e32 v77, 16, v77
	v_add3_u32 v80, v94, v80, s22
	s_and_b32 s6, s6, 0x1f00
	s_and_b32 s11, s11, 0x60
	v_and_or_b32 v80, v80, s23, v77
	s_waitcnt lgkmcnt(1)
	v_bfe_u32 v77, v96, 16, 1
	s_or_b32 s6, s11, s6
	v_add3_u32 v77, v96, v77, s22
	s_waitcnt lgkmcnt(0)
	v_bfe_u32 v81, v98, 16, 1
	s_or_b32 s11, s6, 0x80
	s_lshr_b32 s6, s10, 15
	v_lshrrev_b32_e32 v77, 16, v77
	v_add3_u32 v81, v98, v81, s22
	s_and_b32 s6, s6, 0x1ff80
	v_and_or_b32 v81, v81, s23, v77
	v_or_b32_e32 v77, s11, v199
	v_lshl_add_u64 v[84:85], v[68:69], 0, s[6:7]
	v_lshlrev_b32_e32 v100, 11, v77
	v_mov_b32_e32 v101, v67
	v_lshl_add_u64 v[100:101], v[84:85], 0, v[100:101]
	v_bfe_u32 v77, v83, 16, 1
	global_store_dwordx4 v[100:101], v[78:81], off sc1
	v_add3_u32 v77, v83, v77, s22
	v_lshrrev_b32_e32 v77, 16, v77
	v_bfe_u32 v78, v87, 16, 1
	v_add3_u32 v78, v87, v78, s22
	v_and_or_b32 v78, v78, s23, v77
	v_bfe_u32 v77, v89, 16, 1
	v_add3_u32 v77, v89, v77, s22
	v_bfe_u32 v79, v91, 16, 1
	v_lshrrev_b32_e32 v77, 16, v77
	v_add3_u32 v79, v91, v79, s22
	v_and_or_b32 v79, v79, s23, v77
	v_bfe_u32 v77, v93, 16, 1
	v_add3_u32 v77, v93, v77, s22
	v_bfe_u32 v80, v95, 16, 1
	v_lshrrev_b32_e32 v77, 16, v77
	v_add3_u32 v80, v95, v80, s22
	v_and_or_b32 v80, v80, s23, v77
	v_bfe_u32 v77, v97, 16, 1
	v_add3_u32 v77, v97, v77, s22
	v_bfe_u32 v81, v99, 16, 1
	v_lshrrev_b32_e32 v77, 16, v77
	v_add3_u32 v81, v99, v81, s22
	v_and_or_b32 v81, v81, s23, v77
	v_or_b32_e32 v77, s11, v227
	v_lshlrev_b32_e32 v82, 11, v77
	v_mov_b32_e32 v83, v67
	ds_read2_b32 v[86:87], v75 offset0:16 offset1:24
	v_lshl_add_u64 v[82:83], v[84:85], 0, v[82:83]
	global_store_dwordx4 v[82:83], v[78:81], off sc1
	ds_read2_b32 v[82:83], v75 offset0:49 offset1:57
	ds_read2_b32 v[88:89], v75 offset0:82 offset1:90
	ds_read2_b32 v[90:91], v75 offset0:115 offset1:123
	s_waitcnt lgkmcnt(3)
	v_bfe_u32 v77, v86, 16, 1
	v_add3_u32 v77, v86, v77, s22
	s_waitcnt lgkmcnt(2)
	v_bfe_u32 v78, v82, 16, 1
	ds_read2_b32 v[92:93], v75 offset0:148 offset1:156
	v_lshrrev_b32_e32 v77, 16, v77
	v_add3_u32 v78, v82, v78, s22
	ds_read2_b32 v[94:95], v75 offset0:181 offset1:189
	v_and_or_b32 v78, v78, s23, v77
	s_waitcnt lgkmcnt(3)
	v_bfe_u32 v77, v88, 16, 1
	v_add3_u32 v77, v88, v77, s22
	s_waitcnt lgkmcnt(2)
	v_bfe_u32 v79, v90, 16, 1
	ds_read2_b32 v[96:97], v75 offset0:214 offset1:222
	v_lshrrev_b32_e32 v77, 16, v77
	v_add3_u32 v79, v90, v79, s22
	ds_read2_b32 v[98:99], v75 offset0:247 offset1:255
	v_and_or_b32 v79, v79, s23, v77
	s_waitcnt lgkmcnt(3)
	v_bfe_u32 v77, v92, 16, 1
	v_add3_u32 v77, v92, v77, s22
	s_waitcnt lgkmcnt(2)
	v_bfe_u32 v80, v94, 16, 1
	v_lshrrev_b32_e32 v77, 16, v77
	v_add3_u32 v80, v94, v80, s22
	v_and_or_b32 v80, v80, s23, v77
	s_waitcnt lgkmcnt(1)
	v_bfe_u32 v77, v96, 16, 1
	v_add3_u32 v77, v96, v77, s22
	s_waitcnt lgkmcnt(0)
	v_bfe_u32 v81, v98, 16, 1
	v_lshrrev_b32_e32 v77, 16, v77
	v_add3_u32 v81, v98, v81, s22
	v_and_or_b32 v81, v81, s23, v77
	v_or_b32_e32 v77, s11, v228
	v_lshlrev_b32_e32 v100, 11, v77
	v_mov_b32_e32 v101, v67
	v_lshl_add_u64 v[100:101], v[84:85], 0, v[100:101]
	v_bfe_u32 v77, v87, 16, 1
	global_store_dwordx4 v[100:101], v[78:81], off sc1
	v_add3_u32 v77, v87, v77, s22
	v_lshrrev_b32_e32 v77, 16, v77
	v_bfe_u32 v78, v83, 16, 1
	v_add3_u32 v78, v83, v78, s22
	v_and_or_b32 v78, v78, s23, v77
	v_bfe_u32 v77, v89, 16, 1
	v_add3_u32 v77, v89, v77, s22
	v_bfe_u32 v79, v91, 16, 1
	v_lshrrev_b32_e32 v77, 16, v77
	v_add3_u32 v79, v91, v79, s22
	v_and_or_b32 v79, v79, s23, v77
	v_bfe_u32 v77, v93, 16, 1
	v_add3_u32 v77, v93, v77, s22
	v_bfe_u32 v80, v95, 16, 1
	v_lshrrev_b32_e32 v77, 16, v77
	v_add3_u32 v80, v95, v80, s22
	v_and_or_b32 v80, v80, s23, v77
	v_bfe_u32 v77, v97, 16, 1
	v_add3_u32 v77, v97, v77, s22
	v_bfe_u32 v81, v99, 16, 1
	v_lshrrev_b32_e32 v77, 16, v77
	v_add3_u32 v81, v99, v81, s22
	v_and_or_b32 v81, v81, s23, v77
	v_or_b32_e32 v77, s11, v229
	v_lshlrev_b32_e32 v82, 11, v77
	v_mov_b32_e32 v83, v67
	v_lshl_add_u64 v[82:83], v[84:85], 0, v[82:83]
	global_store_dwordx4 v[82:83], v[78:81], off sc1
	s_waitcnt lgkmcnt(0)
	s_mov_b64 s[10:11], 0

.LBB0_1025:
	s_andn2_b64 vcc, exec, s[10:11]
	s_cbranch_vccnz .LBB0_1027
	v_add_u32_e32 v77, v203, v226
	v_add_u32_e32 v78, 0x420, v77
	s_waitcnt vmcnt(15)
	ds_write2_b32 v77, v54, v55 offset1:1
	ds_write2_b32 v77, v56, v57 offset0:2 offset1:3
	s_waitcnt vmcnt(14)
	ds_write2_b32 v78, v50, v51 offset1:1
	v_add_u32_e32 v78, 0x428, v77
	ds_write2_b32 v78, v52, v53 offset1:1
	v_add_u32_e32 v78, 0x840, v77
	s_waitcnt vmcnt(13)
	ds_write2_b32 v78, v42, v43 offset1:1
	v_add_u32_e32 v78, 0x848, v77
	ds_write2_b32 v78, v44, v45 offset1:1
	v_add_u32_e32 v78, 0xc60, v77
	s_waitcnt vmcnt(12)
	ds_write2_b32 v78, v30, v31 offset1:1
	v_add_u32_e32 v78, 0xc68, v77
	ds_write2_b32 v78, v32, v33 offset1:1
	v_add_u32_e32 v78, 0x1080, v77
	s_waitcnt vmcnt(11)
	ds_write2_b32 v78, v34, v35 offset1:1
	v_add_u32_e32 v78, 0x1088, v77
	ds_write2_b32 v78, v36, v37 offset1:1
	v_add_u32_e32 v78, 0x14a0, v77
	s_waitcnt vmcnt(10)
	ds_write2_b32 v78, v22, v23 offset1:1
	v_add_u32_e32 v78, 0x14a8, v77
	ds_write2_b32 v78, v24, v25 offset1:1
	v_add_u32_e32 v78, 0x18c0, v77
	s_waitcnt vmcnt(9)
	ds_write2_b32 v78, v26, v27 offset1:1
	v_add_u32_e32 v78, 0x18c8, v77
	ds_write2_b32 v78, v28, v29 offset1:1
	v_add_u32_e32 v78, 0x1ce0, v77
	v_add_u32_e32 v77, 0x1ce8, v77
	s_waitcnt vmcnt(8)
	ds_write2_b32 v78, v10, v11 offset1:1
	ds_write2_b32 v77, v12, v13 offset1:1
	s_waitcnt lgkmcnt(0)
	ds_read2_b32 v[82:83], v75 offset1:8
	ds_read2_b32 v[86:87], v75 offset0:33 offset1:41
	ds_read2_b32 v[88:89], v75 offset0:66 offset1:74
	ds_read2_b32 v[90:91], v75 offset0:99 offset1:107
	ds_read2_b32 v[92:93], v75 offset0:132 offset1:140
	s_waitcnt lgkmcnt(4)
	v_bfe_u32 v77, v82, 16, 1
	v_add3_u32 v77, v82, v77, s22
	s_waitcnt lgkmcnt(3)
	v_bfe_u32 v78, v86, 16, 1
	v_lshrrev_b32_e32 v77, 16, v77
	v_add3_u32 v78, v86, v78, s22
	ds_read2_b32 v[94:95], v75 offset0:165 offset1:173
	v_and_or_b32 v78, v78, s23, v77
	s_waitcnt lgkmcnt(3)
	v_bfe_u32 v77, v88, 16, 1
	v_add3_u32 v77, v88, v77, s22
	s_waitcnt lgkmcnt(2)
	v_bfe_u32 v79, v90, 16, 1
	ds_read2_b32 v[96:97], v75 offset0:198 offset1:206
	v_lshrrev_b32_e32 v77, 16, v77
	v_add3_u32 v79, v90, v79, s22
	ds_read2_b32 v[98:99], v75 offset0:231 offset1:239
	v_and_or_b32 v79, v79, s23, v77
	s_waitcnt lgkmcnt(3)
	v_bfe_u32 v77, v92, 16, 1
	v_add3_u32 v77, v92, v77, s22
	s_waitcnt lgkmcnt(2)
	v_bfe_u32 v80, v94, 16, 1
	v_lshrrev_b32_e32 v77, 16, v77
	v_add3_u32 v80, v94, v80, s22
	v_and_or_b32 v80, v80, s23, v77
	s_waitcnt lgkmcnt(1)
	v_bfe_u32 v77, v96, 16, 1
	s_add_i32 s6, s20, 0xffff4000
	v_add3_u32 v77, v96, v77, s22
	s_waitcnt lgkmcnt(0)
	v_bfe_u32 v81, v98, 16, 1
	s_and_b32 s10, s21, 0xfc0
	s_and_b32 s11, s6, 0x3e0
	v_lshrrev_b32_e32 v77, 16, v77
	v_add3_u32 v81, v98, v81, s22
	s_lshl_b32 s6, s10, 1
	v_and_or_b32 v81, v81, s23, v77
	v_or_b32_e32 v77, s11, v199
	v_lshl_add_u64 v[84:85], v[70:71], 0, s[6:7]
	v_lshlrev_b32_e32 v100, 11, v77
	v_mov_b32_e32 v101, v67
	v_lshl_add_u64 v[100:101], v[84:85], 0, v[100:101]
	v_bfe_u32 v77, v83, 16, 1
	global_store_dwordx4 v[100:101], v[78:81], off sc1
	v_add3_u32 v77, v83, v77, s22
	v_lshrrev_b32_e32 v77, 16, v77
	v_bfe_u32 v78, v87, 16, 1
	v_add3_u32 v78, v87, v78, s22
	v_and_or_b32 v78, v78, s23, v77
	v_bfe_u32 v77, v89, 16, 1
	v_add3_u32 v77, v89, v77, s22
	v_bfe_u32 v79, v91, 16, 1
	v_lshrrev_b32_e32 v77, 16, v77
	v_add3_u32 v79, v91, v79, s22
	v_and_or_b32 v79, v79, s23, v77
	v_bfe_u32 v77, v93, 16, 1
	v_add3_u32 v77, v93, v77, s22
	v_bfe_u32 v80, v95, 16, 1
	v_lshrrev_b32_e32 v77, 16, v77
	v_add3_u32 v80, v95, v80, s22
	v_and_or_b32 v80, v80, s23, v77
	v_bfe_u32 v77, v97, 16, 1
	v_add3_u32 v77, v97, v77, s22
	v_bfe_u32 v81, v99, 16, 1
	v_lshrrev_b32_e32 v77, 16, v77
	v_add3_u32 v81, v99, v81, s22
	v_and_or_b32 v81, v81, s23, v77
	v_or_b32_e32 v77, s11, v227
	v_lshlrev_b32_e32 v82, 11, v77
	v_mov_b32_e32 v83, v67
	ds_read2_b32 v[86:87], v75 offset0:16 offset1:24
	v_lshl_add_u64 v[82:83], v[84:85], 0, v[82:83]
	global_store_dwordx4 v[82:83], v[78:81], off sc1
	ds_read2_b32 v[82:83], v75 offset0:49 offset1:57
	ds_read2_b32 v[88:89], v75 offset0:82 offset1:90
	ds_read2_b32 v[90:91], v75 offset0:115 offset1:123
	s_waitcnt lgkmcnt(3)
	v_bfe_u32 v77, v86, 16, 1
	v_add3_u32 v77, v86, v77, s22
	s_waitcnt lgkmcnt(2)
	v_bfe_u32 v78, v82, 16, 1
	ds_read2_b32 v[92:93], v75 offset0:148 offset1:156
	v_lshrrev_b32_e32 v77, 16, v77
	v_add3_u32 v78, v82, v78, s22
	ds_read2_b32 v[94:95], v75 offset0:181 offset1:189
	v_and_or_b32 v78, v78, s23, v77
	s_waitcnt lgkmcnt(3)
	v_bfe_u32 v77, v88, 16, 1
	v_add3_u32 v77, v88, v77, s22
	s_waitcnt lgkmcnt(2)
	v_bfe_u32 v79, v90, 16, 1
	ds_read2_b32 v[96:97], v75 offset0:214 offset1:222
	v_lshrrev_b32_e32 v77, 16, v77
	v_add3_u32 v79, v90, v79, s22
	ds_read2_b32 v[98:99], v75 offset0:247 offset1:255
	v_and_or_b32 v79, v79, s23, v77
	s_waitcnt lgkmcnt(3)
	v_bfe_u32 v77, v92, 16, 1
	v_add3_u32 v77, v92, v77, s22
	s_waitcnt lgkmcnt(2)
	v_bfe_u32 v80, v94, 16, 1
	v_lshrrev_b32_e32 v77, 16, v77
	v_add3_u32 v80, v94, v80, s22
	v_and_or_b32 v80, v80, s23, v77
	s_waitcnt lgkmcnt(1)
	v_bfe_u32 v77, v96, 16, 1
	v_add3_u32 v77, v96, v77, s22
	s_waitcnt lgkmcnt(0)
	v_bfe_u32 v81, v98, 16, 1
	v_lshrrev_b32_e32 v77, 16, v77
	v_add3_u32 v81, v98, v81, s22
	v_and_or_b32 v81, v81, s23, v77
	v_or_b32_e32 v77, s11, v228
	v_lshlrev_b32_e32 v100, 11, v77
	v_mov_b32_e32 v101, v67
	v_lshl_add_u64 v[100:101], v[84:85], 0, v[100:101]
	v_bfe_u32 v77, v87, 16, 1
	global_store_dwordx4 v[100:101], v[78:81], off sc1
	v_add3_u32 v77, v87, v77, s22
	v_lshrrev_b32_e32 v77, 16, v77
	v_bfe_u32 v78, v83, 16, 1
	v_add3_u32 v78, v83, v78, s22
	v_and_or_b32 v78, v78, s23, v77
	v_bfe_u32 v77, v89, 16, 1
	v_add3_u32 v77, v89, v77, s22
	v_bfe_u32 v79, v91, 16, 1
	v_lshrrev_b32_e32 v77, 16, v77
	v_add3_u32 v79, v91, v79, s22
	v_and_or_b32 v79, v79, s23, v77
	v_bfe_u32 v77, v93, 16, 1
	v_add3_u32 v77, v93, v77, s22
	v_bfe_u32 v80, v95, 16, 1
	v_lshrrev_b32_e32 v77, 16, v77
	v_add3_u32 v80, v95, v80, s22
	v_and_or_b32 v80, v80, s23, v77
	v_bfe_u32 v77, v97, 16, 1
	v_add3_u32 v77, v97, v77, s22
	v_bfe_u32 v81, v99, 16, 1
	v_lshrrev_b32_e32 v77, 16, v77
	v_add3_u32 v81, v99, v81, s22
	v_and_or_b32 v81, v81, s23, v77
	v_or_b32_e32 v77, s11, v229
	v_lshlrev_b32_e32 v82, 11, v77
	v_mov_b32_e32 v83, v67
	v_lshl_add_u64 v[82:83], v[84:85], 0, v[82:83]
	global_store_dwordx4 v[82:83], v[78:81], off sc1
	s_waitcnt lgkmcnt(0)

.LBB0_1033:
	s_mul_hi_i32 s6, s25, 0x2aaaaaab
	s_lshr_b32 s10, s6, 31
	s_ashr_i32 s6, s6, 4
	s_add_i32 s6, s6, s10
	s_mul_i32 s10, s6, 0xffffffa0
	s_add_i32 s11, s25, s10
	s_lshl_b32 s10, s6, 6
	s_cmp_lt_i32 s11, 16
	s_cselect_b64 vcc, -1, 0
	v_cndmask_b32_e32 v78, 1.0, v76, vcc
	s_waitcnt vmcnt(15)
	v_pk_mul_f32 v[54:55], v[78:79], v[54:55] op_sel_hi:[0,1]
	v_add_u32_e32 v77, v203, v226
	ds_write2_b32 v77, v54, v55 offset1:1
	v_pk_mul_f32 v[54:55], v[78:79], v[56:57] op_sel_hi:[0,1]
	ds_write2_b32 v77, v54, v55 offset0:2 offset1:3
	s_waitcnt vmcnt(14)
	v_pk_mul_f32 v[50:51], v[78:79], v[50:51] op_sel_hi:[0,1]
	v_add_u32_e32 v54, 0x420, v77
	ds_write2_b32 v54, v50, v51 offset1:1
	v_pk_mul_f32 v[50:51], v[78:79], v[52:53] op_sel_hi:[0,1]
	v_add_u32_e32 v52, 0x428, v77
	ds_write2_b32 v52, v50, v51 offset1:1
	s_waitcnt vmcnt(13)
	v_pk_mul_f32 v[42:43], v[78:79], v[42:43] op_sel_hi:[0,1]
	v_add_u32_e32 v50, 0x840, v77
	ds_write2_b32 v50, v42, v43 offset1:1
	v_pk_mul_f32 v[42:43], v[78:79], v[44:45] op_sel_hi:[0,1]
	v_add_u32_e32 v44, 0x848, v77
	ds_write2_b32 v44, v42, v43 offset1:1
	s_waitcnt vmcnt(12)
	v_pk_mul_f32 v[30:31], v[78:79], v[30:31] op_sel_hi:[0,1]
	v_add_u32_e32 v42, 0xc60, v77
	ds_write2_b32 v42, v30, v31 offset1:1
	v_pk_mul_f32 v[30:31], v[78:79], v[32:33] op_sel_hi:[0,1]
	v_add_u32_e32 v32, 0xc68, v77
	ds_write2_b32 v32, v30, v31 offset1:1
	s_waitcnt vmcnt(11)
	v_pk_mul_f32 v[30:31], v[78:79], v[34:35] op_sel_hi:[0,1]
	v_add_u32_e32 v32, 0x1080, v77
	ds_write2_b32 v32, v30, v31 offset1:1
	v_pk_mul_f32 v[30:31], v[78:79], v[36:37] op_sel_hi:[0,1]
	v_add_u32_e32 v32, 0x1088, v77
	ds_write2_b32 v32, v30, v31 offset1:1
	s_waitcnt vmcnt(10)
	v_pk_mul_f32 v[22:23], v[78:79], v[22:23] op_sel_hi:[0,1]
	v_add_u32_e32 v30, 0x14a0, v77
	ds_write2_b32 v30, v22, v23 offset1:1
	v_pk_mul_f32 v[22:23], v[78:79], v[24:25] op_sel_hi:[0,1]
	v_add_u32_e32 v24, 0x14a8, v77
	ds_write2_b32 v24, v22, v23 offset1:1
	s_waitcnt vmcnt(9)
	v_pk_mul_f32 v[22:23], v[26:27], v[78:79] op_sel_hi:[1,0]
	v_add_u32_e32 v24, 0x18c0, v77
	ds_write2_b32 v24, v22, v23 offset1:1
	v_pk_mul_f32 v[22:23], v[28:29], v[78:79] op_sel_hi:[1,0]
	v_add_u32_e32 v24, 0x18c8, v77
	ds_write2_b32 v24, v22, v23 offset1:1
	s_waitcnt vmcnt(8)
	v_pk_mul_f32 v[10:11], v[10:11], v[78:79] op_sel_hi:[1,0]
	v_add_u32_e32 v22, 0x1ce0, v77
	ds_write2_b32 v22, v10, v11 offset1:1
	v_pk_mul_f32 v[10:11], v[12:13], v[78:79] op_sel_hi:[1,0]
	v_add_u32_e32 v12, 0x1ce8, v77
	ds_write2_b32 v12, v10, v11 offset1:1
	s_waitcnt lgkmcnt(0)
	ds_read2_b32 v[22:23], v75 offset1:8
	ds_read2_b32 v[26:27], v75 offset0:33 offset1:41
	ds_read2_b32 v[28:29], v75 offset0:66 offset1:74
	ds_read2_b32 v[30:31], v75 offset0:99 offset1:107
	ds_read2_b32 v[32:33], v75 offset0:132 offset1:140
	s_waitcnt lgkmcnt(4)
	v_bfe_u32 v10, v22, 16, 1
	v_add3_u32 v10, v22, v10, s22
	s_waitcnt lgkmcnt(3)
	v_bfe_u32 v11, v26, 16, 1
	v_lshrrev_b32_e32 v10, 16, v10
	v_add3_u32 v11, v26, v11, s22
	ds_read2_b32 v[34:35], v75 offset0:165 offset1:173
	v_and_or_b32 v10, v11, s23, v10
	s_waitcnt lgkmcnt(3)
	v_bfe_u32 v11, v28, 16, 1
	v_add3_u32 v11, v28, v11, s22
	s_waitcnt lgkmcnt(2)
	v_bfe_u32 v12, v30, 16, 1
	ds_read2_b32 v[36:37], v75 offset0:198 offset1:206
	v_lshrrev_b32_e32 v11, 16, v11
	v_add3_u32 v12, v30, v12, s22
	ds_read2_b32 v[42:43], v75 offset0:231 offset1:239
	v_and_or_b32 v11, v12, s23, v11
	s_waitcnt lgkmcnt(3)
	v_bfe_u32 v12, v32, 16, 1
	v_add3_u32 v12, v32, v12, s22
	s_waitcnt lgkmcnt(2)
	v_bfe_u32 v13, v34, 16, 1
	s_mulk_i32 s6, 0xf400
	v_lshrrev_b32_e32 v12, 16, v12
	v_add3_u32 v13, v34, v13, s22
	s_add_i32 s6, s6, s20
	v_and_or_b32 v12, v13, s23, v12
	s_waitcnt lgkmcnt(1)
	v_bfe_u32 v13, v36, 16, 1
	v_add_u32_e32 v44, s6, v199
	s_ashr_i32 s11, s10, 31
	v_add3_u32 v13, v36, v13, s22
	s_waitcnt lgkmcnt(0)
	v_bfe_u32 v22, v42, 16, 1
	v_ashrrev_i32_e32 v45, 31, v44
	v_lshl_add_u64 v[24:25], s[10:11], 1, v[72:73]
	v_lshrrev_b32_e32 v13, 16, v13
	v_add3_u32 v22, v42, v22, s22
	v_lshlrev_b64 v[50:51], 11, v[44:45]
	v_and_or_b32 v13, v22, s23, v13
	v_lshl_add_u64 v[50:51], v[24:25], 0, v[50:51]
	global_store_dwordx4 v[50:51], v[10:13], off sc1
	v_bfe_u32 v22, v43, 16, 1
	v_add3_u32 v22, v43, v22, s22
	v_bfe_u32 v10, v23, 16, 1
	v_add3_u32 v10, v23, v10, s22
	v_bfe_u32 v11, v27, 16, 1
	v_lshrrev_b32_e32 v10, 16, v10
	v_add3_u32 v11, v27, v11, s22
	v_and_or_b32 v10, v11, s23, v10
	v_bfe_u32 v11, v29, 16, 1
	v_add3_u32 v11, v29, v11, s22
	v_bfe_u32 v12, v31, 16, 1
	v_lshrrev_b32_e32 v11, 16, v11
	v_add3_u32 v12, v31, v12, s22
	v_and_or_b32 v11, v12, s23, v11
	v_bfe_u32 v12, v33, 16, 1
	v_add3_u32 v12, v33, v12, s22
	v_bfe_u32 v13, v35, 16, 1
	v_lshrrev_b32_e32 v12, 16, v12
	v_add3_u32 v13, v35, v13, s22
	v_and_or_b32 v12, v13, s23, v12
	v_bfe_u32 v13, v37, 16, 1
	v_add3_u32 v13, v37, v13, s22
	v_lshrrev_b32_e32 v13, 16, v13
	v_and_or_b32 v13, v22, s23, v13
	v_add_u32_e32 v22, 8, v44
	v_ashrrev_i32_e32 v23, 31, v22
	v_lshlrev_b64 v[22:23], 11, v[22:23]
	ds_read2_b32 v[26:27], v75 offset0:16 offset1:24
	v_lshl_add_u64 v[22:23], v[24:25], 0, v[22:23]
	global_store_dwordx4 v[22:23], v[10:13], off sc1
	ds_read2_b32 v[22:23], v75 offset0:49 offset1:57
	ds_read2_b32 v[28:29], v75 offset0:82 offset1:90
	ds_read2_b32 v[30:31], v75 offset0:115 offset1:123
	s_waitcnt lgkmcnt(3)
	v_bfe_u32 v10, v26, 16, 1
	v_add3_u32 v10, v26, v10, s22
	s_waitcnt lgkmcnt(2)
	v_bfe_u32 v11, v22, 16, 1
	ds_read2_b32 v[32:33], v75 offset0:148 offset1:156
	v_lshrrev_b32_e32 v10, 16, v10
	v_add3_u32 v11, v22, v11, s22
	ds_read2_b32 v[34:35], v75 offset0:181 offset1:189
	v_and_or_b32 v10, v11, s23, v10
	s_waitcnt lgkmcnt(3)
	v_bfe_u32 v11, v28, 16, 1
	v_add3_u32 v11, v28, v11, s22
	s_waitcnt lgkmcnt(2)
	v_bfe_u32 v12, v30, 16, 1
	ds_read2_b32 v[36:37], v75 offset0:214 offset1:222
	v_lshrrev_b32_e32 v11, 16, v11
	v_add3_u32 v12, v30, v12, s22
	ds_read2_b32 v[42:43], v75 offset0:247 offset1:255
	v_and_or_b32 v11, v12, s23, v11
	s_waitcnt lgkmcnt(3)
	v_bfe_u32 v12, v32, 16, 1
	v_add3_u32 v12, v32, v12, s22
	s_waitcnt lgkmcnt(2)
	v_bfe_u32 v13, v34, 16, 1
	v_lshrrev_b32_e32 v12, 16, v12
	v_add3_u32 v13, v34, v13, s22
	v_and_or_b32 v12, v13, s23, v12
	s_waitcnt lgkmcnt(1)
	v_bfe_u32 v13, v36, 16, 1
	v_add_u32_e32 v50, 16, v44
	v_add3_u32 v13, v36, v13, s22
	s_waitcnt lgkmcnt(0)
	v_bfe_u32 v22, v42, 16, 1
	v_ashrrev_i32_e32 v51, 31, v50
	v_lshrrev_b32_e32 v13, 16, v13
	v_add3_u32 v22, v42, v22, s22
	v_lshlrev_b64 v[50:51], 11, v[50:51]
	v_and_or_b32 v13, v22, s23, v13
	v_lshl_add_u64 v[50:51], v[24:25], 0, v[50:51]
	global_store_dwordx4 v[50:51], v[10:13], off sc1
	v_bfe_u32 v22, v43, 16, 1
	v_add3_u32 v22, v43, v22, s22
	v_bfe_u32 v10, v27, 16, 1
	v_add3_u32 v10, v27, v10, s22
	v_bfe_u32 v11, v23, 16, 1
	v_lshrrev_b32_e32 v10, 16, v10
	v_add3_u32 v11, v23, v11, s22
	v_and_or_b32 v10, v11, s23, v10
	v_bfe_u32 v11, v29, 16, 1
	v_add3_u32 v11, v29, v11, s22
	v_bfe_u32 v12, v31, 16, 1
	v_lshrrev_b32_e32 v11, 16, v11
	v_add3_u32 v12, v31, v12, s22
	v_and_or_b32 v11, v12, s23, v11
	v_bfe_u32 v12, v33, 16, 1
	v_add3_u32 v12, v33, v12, s22
	v_bfe_u32 v13, v35, 16, 1
	v_lshrrev_b32_e32 v12, 16, v12
	v_add3_u32 v13, v35, v13, s22
	v_and_or_b32 v12, v13, s23, v12
	v_bfe_u32 v13, v37, 16, 1
	v_add3_u32 v13, v37, v13, s22
	v_lshrrev_b32_e32 v13, 16, v13
	v_and_or_b32 v13, v22, s23, v13
	v_add_u32_e32 v22, 24, v44
	v_ashrrev_i32_e32 v23, 31, v22
	v_lshlrev_b64 v[22:23], 11, v[22:23]
	v_lshl_add_u64 v[22:23], v[24:25], 0, v[22:23]
	global_store_dwordx4 v[22:23], v[10:13], off sc1
	s_waitcnt lgkmcnt(0)
	s_branch .LBB0_1012
